# r45 + NSA compressed-KV staging loop: all (up to 4) iterations' global loads issued up front, single wait, then convert+LDS store
# baseline (speedup 1.0000x reference)
.Lnsa_prio_skip:
	s_sub_i32 s0, s3, 64
	s_lshl_b32 s1, s3, 5
	s_and_b32 s1, s1, 0x1e0
	s_lshr_b32 s0, s0, 4
	s_sub_i32 s0, s1, s0
	s_add_i32 s0, s0, 31
	v_mov_b32_e32 v1, v182
	s_and_b32 s78, s0, 31
	v_and_b32_e32 v66, 31, v1
	s_waitcnt vmcnt(2)
	v_lshrrev_b32_e32 v15, 1, v1
	s_lshl_b32 s2, s78, 6
	v_and_or_b32 v68, v15, 32, v66
	s_lshr_b32 s88, s0, 5
	v_ashrrev_i32_e32 v71, 7, v1
	v_or_b32_e32 v67, s2, v68
	v_lshl_or_b32 v108, s88, 11, v67
	v_mov_b64_e32 v[2:3], s[58:59]
	s_movk_i32 s0, 0x1e00
	s_waitcnt vmcnt(0)
	v_lshlrev_b32_e32 v112, 6, v71
	v_bfe_u32 v69, v1, 5, 1
	v_mad_u64_u32 v[110:111], s[0:1], v108, s0, v[2:3]
	v_ashrrev_i32_e32 v113, 31, v112
	v_lshl_add_u64 v[2:3], v[112:113], 1, v[110:111]
	v_lshlrev_b32_e32 v4, 4, v69
	v_mov_b32_e32 v5, v0
	v_lshl_add_u64 v[2:3], v[2:3], 0, v[4:5]
	s_mov_b64 s[0:1], 0x1700
	v_mov_b32_e32 v109, v0
	v_lshl_add_u64 v[4:5], v[2:3], 0, s[0:1]
	v_add_co_u32_e32 v2, vcc, s86, v2
	s_addk_i32 s2, 0x220
	s_nop 0
	v_addc_co_u32_e32 v3, vcc, 0, v3, vcc
	global_load_dwordx4 v[80:83], v[4:5], off offset:32
	global_load_dwordx4 v[84:87], v[4:5], off offset:64
	global_load_dwordx4 v[88:91], v[2:3], off offset:1792
	global_load_dwordx4 v[92:95], v[4:5], off offset:96
	v_lshl_add_u32 v2, v71, 1, v71
	v_lshlrev_b64 v[4:5], 7, v[108:109]
	v_ashrrev_i32_e32 v3, 31, v2
	v_lshl_add_u64 v[4:5], s[60:61], 0, v[4:5]
	v_lshl_add_u64 v[2:3], v[2:3], 2, v[4:5]
	global_load_dwordx3 v[104:106], v[2:3], off offset:32
	s_and_b32 s6, s2, 0xe00
	v_writelane_b32 v254, s3, 23
	v_cmp_gt_i32_e32 vcc, s6, v1
	s_and_saveexec_b64 s[0:1], vcc
	s_cbranch_execz .LBB0_683
	s_lshl_b32 s2, s78, 2
	s_or_b32 s7, s2, 3
	s_lshl_b32 s2, s88, 15
	s_add_u32 s2, s66, s2
	v_and_b32_e32 v6, 15, v1
	s_addc_u32 s3, s67, 0
	s_lshl_b64 s[4:5], s[88:89], 15
	v_lshlrev_b32_e32 v2, 4, v6
	v_mov_b32_e32 v3, v0
	s_add_u32 s4, s66, s4
	v_lshl_add_u64 v[4:5], s[2:3], 0, v[2:3]
	s_mov_b64 s[2:3], 0x80000
	s_addc_u32 s5, s67, s5
	v_lshl_add_u64 v[10:11], v[4:5], 0, s[2:3]
	v_readlane_b32 s2, v253, 20
	v_lshl_add_u64 v[12:13], s[4:5], 0, v[2:3]
	v_lshl_add_u32 v14, v6, 3, 0
	v_mov_b32_e32 v2, s2
	s_movk_i32 s2, 0x420
	s_waitcnt vmcnt(6)
	v_mad_u32_u24 v16, v6, s2, v2
	v_ashrrev_i32_e32 v197, 4, v1
	v_mov_b32_e32 v218, 0
	v_mov_b32_e32 v219, 0
	v_mov_b32_e32 v220, 0
	v_mov_b32_e32 v221, 0
	v_mov_b32_e32 v222, 0
	v_mov_b32_e32 v223, 0
	v_mov_b32_e32 v224, 0
	v_mov_b32_e32 v225, 0
	v_cmp_gt_i32_e32 vcc, s7, v197
	s_and_saveexec_b64 s[4:5], vcc
	v_lshlrev_b32_e32 v20, 6, v197
	v_ashrrev_i32_e32 v21, 31, v20
	v_lshlrev_b64 v[20:21], 2, v[20:21]
	v_lshl_add_u64 v[22:23], v[12:13], 0, v[20:21]
	v_lshl_add_u64 v[20:21], v[10:11], 0, v[20:21]
	global_load_dwordx4 v[218:221], v[22:23], off
	global_load_dwordx4 v[222:225], v[20:21], off
	s_or_b64 exec, exec, s[4:5]
	s_cmp_gt_u32 s6, 0x200
	s_cbranch_scc0 .Lnsakc_lddone
	v_add_u32_e32 v198, 32, v197
	v_mov_b32_e32 v226, 0
	v_mov_b32_e32 v227, 0
	v_mov_b32_e32 v228, 0
	v_mov_b32_e32 v229, 0
	v_mov_b32_e32 v230, 0
	v_mov_b32_e32 v231, 0
	v_mov_b32_e32 v232, 0
	v_mov_b32_e32 v233, 0
	v_cmp_gt_i32_e32 vcc, s7, v198
	s_and_saveexec_b64 s[4:5], vcc
	v_lshlrev_b32_e32 v20, 6, v198
	v_ashrrev_i32_e32 v21, 31, v20
	v_lshlrev_b64 v[20:21], 2, v[20:21]
	v_lshl_add_u64 v[22:23], v[12:13], 0, v[20:21]
	v_lshl_add_u64 v[20:21], v[10:11], 0, v[20:21]
	global_load_dwordx4 v[226:229], v[22:23], off
	global_load_dwordx4 v[230:233], v[20:21], off
	s_or_b64 exec, exec, s[4:5]
	s_cmp_gt_u32 s6, 0x400
	s_cbranch_scc0 .Lnsakc_lddone
	v_add_u32_e32 v199, 64, v197
	v_mov_b32_e32 v234, 0
	v_mov_b32_e32 v235, 0
	v_mov_b32_e32 v236, 0
	v_mov_b32_e32 v237, 0
	v_mov_b32_e32 v238, 0
	v_mov_b32_e32 v239, 0
	v_mov_b32_e32 v240, 0
	v_mov_b32_e32 v241, 0
	v_cmp_gt_i32_e32 vcc, s7, v199
	s_and_saveexec_b64 s[4:5], vcc
	v_lshlrev_b32_e32 v20, 6, v199
	v_ashrrev_i32_e32 v21, 31, v20
	v_lshlrev_b64 v[20:21], 2, v[20:21]
	v_lshl_add_u64 v[22:23], v[12:13], 0, v[20:21]
	v_lshl_add_u64 v[20:21], v[10:11], 0, v[20:21]
	global_load_dwordx4 v[234:237], v[22:23], off
	global_load_dwordx4 v[238:241], v[20:21], off
	s_or_b64 exec, exec, s[4:5]
	s_cmp_gt_u32 s6, 0x600
	s_cbranch_scc0 .Lnsakc_lddone
	v_add_u32_e32 v200, 96, v197
	v_mov_b32_e32 v242, 0
	v_mov_b32_e32 v243, 0
	v_mov_b32_e32 v244, 0
	v_mov_b32_e32 v245, 0
	v_mov_b32_e32 v246, 0
	v_mov_b32_e32 v247, 0
	v_mov_b32_e32 v248, 0
	v_mov_b32_e32 v249, 0
	v_cmp_gt_i32_e32 vcc, s7, v200
	s_and_saveexec_b64 s[4:5], vcc
	v_lshlrev_b32_e32 v20, 6, v200
	v_ashrrev_i32_e32 v21, 31, v20
	v_lshlrev_b64 v[20:21], 2, v[20:21]
	v_lshl_add_u64 v[22:23], v[12:13], 0, v[20:21]
	v_lshl_add_u64 v[20:21], v[10:11], 0, v[20:21]
	global_load_dwordx4 v[242:245], v[22:23], off
	global_load_dwordx4 v[246:249], v[20:21], off
	s_or_b64 exec, exec, s[4:5]
.Lnsakc_lddone:
	s_waitcnt vmcnt(0)
	v_and_b32_sdwa v19, v219, v190 dst_sel:DWORD dst_unused:UNUSED_PAD src0_sel:WORD_1 src1_sel:DWORD
	v_and_b32_sdwa v20, v218, v190 dst_sel:DWORD dst_unused:UNUSED_PAD src0_sel:WORD_1 src1_sel:DWORD
	v_add3_u32 v19, v219, v19, s39
	v_add3_u32 v22, v218, v20, s39
	v_and_b32_e32 v21, 0xffff0000, v19
	v_and_b32_e32 v20, 0xffff0000, v22
	v_pk_add_f32 v[6:7], v[218:219], v[20:21] neg_lo:[0,1] neg_hi:[0,1]
	v_and_b32_sdwa v19, v220, v190 dst_sel:DWORD dst_unused:UNUSED_PAD src0_sel:WORD_1 src1_sel:DWORD
	v_cvt_pk_bf16_f32 v6, v6, v7
	v_and_b32_sdwa v7, v221, v190 dst_sel:DWORD dst_unused:UNUSED_PAD src0_sel:WORD_1 src1_sel:DWORD
	v_add3_u32 v7, v221, v7, s39
	v_add3_u32 v19, v220, v19, s39
	v_or_b32_sdwa v22, v21, v22 dst_sel:DWORD dst_unused:UNUSED_PAD src0_sel:DWORD src1_sel:WORD_1
	v_and_b32_e32 v21, 0xffff0000, v7
	v_and_b32_e32 v20, 0xffff0000, v19
	v_pk_add_f32 v[8:9], v[220:221], v[20:21] neg_lo:[0,1] neg_hi:[0,1]
	s_movk_i32 s4, 0x90
	v_or_b32_sdwa v23, v21, v19 dst_sel:DWORD dst_unused:UNUSED_PAD src0_sel:DWORD src1_sel:WORD_1
	v_cvt_pk_bf16_f32 v7, v8, v9
	v_mad_u64_u32 v[8:9], s[4:5], v197, s4, v[14:15]
	ds_write2st64_b64 v8, v[22:23], v[6:7] offset0:70 offset1:106
	v_bfe_u32 v6, v222, 16, 1
	v_add3_u32 v2, v222, v6, s39
	v_lshl_add_u32 v6, v197, 1, v16
	ds_write_b16_d16_hi v6, v2
	v_bfe_u32 v2, v223, 16, 1
	v_add3_u32 v2, v223, v2, s39
	ds_write_b16_d16_hi v6, v2 offset:264
	v_bfe_u32 v2, v224, 16, 1
	v_add3_u32 v2, v224, v2, s39
	ds_write_b16_d16_hi v6, v2 offset:528
	v_bfe_u32 v2, v225, 16, 1
	v_add3_u32 v2, v225, v2, s39
	ds_write_b16_d16_hi v6, v2 offset:792
	s_cmp_gt_u32 s6, 0x200
	s_cbranch_scc0 .LBB0_683
	v_and_b32_sdwa v19, v227, v190 dst_sel:DWORD dst_unused:UNUSED_PAD src0_sel:WORD_1 src1_sel:DWORD
	v_and_b32_sdwa v20, v226, v190 dst_sel:DWORD dst_unused:UNUSED_PAD src0_sel:WORD_1 src1_sel:DWORD
	v_add3_u32 v19, v227, v19, s39
	v_add3_u32 v22, v226, v20, s39
	v_and_b32_e32 v21, 0xffff0000, v19
	v_and_b32_e32 v20, 0xffff0000, v22
	v_pk_add_f32 v[6:7], v[226:227], v[20:21] neg_lo:[0,1] neg_hi:[0,1]
	v_and_b32_sdwa v19, v228, v190 dst_sel:DWORD dst_unused:UNUSED_PAD src0_sel:WORD_1 src1_sel:DWORD
	v_cvt_pk_bf16_f32 v6, v6, v7
	v_and_b32_sdwa v7, v229, v190 dst_sel:DWORD dst_unused:UNUSED_PAD src0_sel:WORD_1 src1_sel:DWORD
	v_add3_u32 v7, v229, v7, s39
	v_add3_u32 v19, v228, v19, s39
	v_or_b32_sdwa v22, v21, v22 dst_sel:DWORD dst_unused:UNUSED_PAD src0_sel:DWORD src1_sel:WORD_1
	v_and_b32_e32 v21, 0xffff0000, v7
	v_and_b32_e32 v20, 0xffff0000, v19
	v_pk_add_f32 v[8:9], v[228:229], v[20:21] neg_lo:[0,1] neg_hi:[0,1]
	s_movk_i32 s4, 0x90
	v_or_b32_sdwa v23, v21, v19 dst_sel:DWORD dst_unused:UNUSED_PAD src0_sel:DWORD src1_sel:WORD_1
	v_cvt_pk_bf16_f32 v7, v8, v9
	v_mad_u64_u32 v[8:9], s[4:5], v198, s4, v[14:15]
	ds_write2st64_b64 v8, v[22:23], v[6:7] offset0:70 offset1:106
	v_bfe_u32 v6, v230, 16, 1
	v_add3_u32 v2, v230, v6, s39
	v_lshl_add_u32 v6, v198, 1, v16
	ds_write_b16_d16_hi v6, v2
	v_bfe_u32 v2, v231, 16, 1
	v_add3_u32 v2, v231, v2, s39
	ds_write_b16_d16_hi v6, v2 offset:264
	v_bfe_u32 v2, v232, 16, 1
	v_add3_u32 v2, v232, v2, s39
	ds_write_b16_d16_hi v6, v2 offset:528
	v_bfe_u32 v2, v233, 16, 1
	v_add3_u32 v2, v233, v2, s39
	ds_write_b16_d16_hi v6, v2 offset:792
	s_cmp_gt_u32 s6, 0x400
	s_cbranch_scc0 .LBB0_683
	v_and_b32_sdwa v19, v235, v190 dst_sel:DWORD dst_unused:UNUSED_PAD src0_sel:WORD_1 src1_sel:DWORD
	v_and_b32_sdwa v20, v234, v190 dst_sel:DWORD dst_unused:UNUSED_PAD src0_sel:WORD_1 src1_sel:DWORD
	v_add3_u32 v19, v235, v19, s39
	v_add3_u32 v22, v234, v20, s39
	v_and_b32_e32 v21, 0xffff0000, v19
	v_and_b32_e32 v20, 0xffff0000, v22
	v_pk_add_f32 v[6:7], v[234:235], v[20:21] neg_lo:[0,1] neg_hi:[0,1]
	v_and_b32_sdwa v19, v236, v190 dst_sel:DWORD dst_unused:UNUSED_PAD src0_sel:WORD_1 src1_sel:DWORD
	v_cvt_pk_bf16_f32 v6, v6, v7
	v_and_b32_sdwa v7, v237, v190 dst_sel:DWORD dst_unused:UNUSED_PAD src0_sel:WORD_1 src1_sel:DWORD
	v_add3_u32 v7, v237, v7, s39
	v_add3_u32 v19, v236, v19, s39
	v_or_b32_sdwa v22, v21, v22 dst_sel:DWORD dst_unused:UNUSED_PAD src0_sel:DWORD src1_sel:WORD_1
	v_and_b32_e32 v21, 0xffff0000, v7
	v_and_b32_e32 v20, 0xffff0000, v19
	v_pk_add_f32 v[8:9], v[236:237], v[20:21] neg_lo:[0,1] neg_hi:[0,1]
	s_movk_i32 s4, 0x90
	v_or_b32_sdwa v23, v21, v19 dst_sel:DWORD dst_unused:UNUSED_PAD src0_sel:DWORD src1_sel:WORD_1
	v_cvt_pk_bf16_f32 v7, v8, v9
	v_mad_u64_u32 v[8:9], s[4:5], v199, s4, v[14:15]
	ds_write2st64_b64 v8, v[22:23], v[6:7] offset0:70 offset1:106
	v_bfe_u32 v6, v238, 16, 1
	v_add3_u32 v2, v238, v6, s39
	v_lshl_add_u32 v6, v199, 1, v16
	ds_write_b16_d16_hi v6, v2
	v_bfe_u32 v2, v239, 16, 1
	v_add3_u32 v2, v239, v2, s39
	ds_write_b16_d16_hi v6, v2 offset:264
	v_bfe_u32 v2, v240, 16, 1
	v_add3_u32 v2, v240, v2, s39
	ds_write_b16_d16_hi v6, v2 offset:528
	v_bfe_u32 v2, v241, 16, 1
	v_add3_u32 v2, v241, v2, s39
	ds_write_b16_d16_hi v6, v2 offset:792
	s_cmp_gt_u32 s6, 0x600
	s_cbranch_scc0 .LBB0_683
	v_and_b32_sdwa v19, v243, v190 dst_sel:DWORD dst_unused:UNUSED_PAD src0_sel:WORD_1 src1_sel:DWORD
	v_and_b32_sdwa v20, v242, v190 dst_sel:DWORD dst_unused:UNUSED_PAD src0_sel:WORD_1 src1_sel:DWORD
	v_add3_u32 v19, v243, v19, s39
	v_add3_u32 v22, v242, v20, s39
	v_and_b32_e32 v21, 0xffff0000, v19
	v_and_b32_e32 v20, 0xffff0000, v22
	v_pk_add_f32 v[6:7], v[242:243], v[20:21] neg_lo:[0,1] neg_hi:[0,1]
	v_and_b32_sdwa v19, v244, v190 dst_sel:DWORD dst_unused:UNUSED_PAD src0_sel:WORD_1 src1_sel:DWORD
	v_cvt_pk_bf16_f32 v6, v6, v7
	v_and_b32_sdwa v7, v245, v190 dst_sel:DWORD dst_unused:UNUSED_PAD src0_sel:WORD_1 src1_sel:DWORD
	v_add3_u32 v7, v245, v7, s39
	v_add3_u32 v19, v244, v19, s39
	v_or_b32_sdwa v22, v21, v22 dst_sel:DWORD dst_unused:UNUSED_PAD src0_sel:DWORD src1_sel:WORD_1
	v_and_b32_e32 v21, 0xffff0000, v7
	v_and_b32_e32 v20, 0xffff0000, v19
	v_pk_add_f32 v[8:9], v[244:245], v[20:21] neg_lo:[0,1] neg_hi:[0,1]
	s_movk_i32 s4, 0x90
	v_or_b32_sdwa v23, v21, v19 dst_sel:DWORD dst_unused:UNUSED_PAD src0_sel:DWORD src1_sel:WORD_1
	v_cvt_pk_bf16_f32 v7, v8, v9
	v_mad_u64_u32 v[8:9], s[4:5], v200, s4, v[14:15]
	ds_write2st64_b64 v8, v[22:23], v[6:7] offset0:70 offset1:106
	v_bfe_u32 v6, v246, 16, 1
	v_add3_u32 v2, v246, v6, s39
	v_lshl_add_u32 v6, v200, 1, v16
	ds_write_b16_d16_hi v6, v2
	v_bfe_u32 v2, v247, 16, 1
	v_add3_u32 v2, v247, v2, s39
	ds_write_b16_d16_hi v6, v2 offset:264
	v_bfe_u32 v2, v248, 16, 1
	v_add3_u32 v2, v248, v2, s39
	ds_write_b16_d16_hi v6, v2 offset:528
	v_bfe_u32 v2, v249, 16, 1
	v_add3_u32 v2, v249, v2, s39
	ds_write_b16_d16_hi v6, v2 offset:792
